# lever 2 epilogue de-serialisation: software-pipelined GEMM epilogue in all 4 live GEMMs (next group's cvt+LDS transpose in flight while previous group's stores issue; addresses via v_lshl_add_u64)
# baseline (speedup 1.0000x reference)
.LBB0_82:
	v_lshl_add_u32 v156, s16, 8, v148
	v_mov_b64_e32 v[154:155], s[56:57]
	s_movk_i32 s11, 0x6080
	v_mad_i64_i32 v[154:155], vcc, v156, s11, v[154:155]
	s_lshl_b32 s20, s94, 8
	s_ashr_i32 s21, s20, 31
	v_lshl_add_u64 v[154:155], s[20:21], 1, v[154:155]
	v_lshl_add_u64 v[154:155], v[154:155], 0, s[0:1]
	s_nop 3
	s_mov_b32 s101, 0
	v_cvt_pk_bf16_f32 v126, v126, v127
	v_cvt_pk_bf16_f32 v127, v128, v129
	v_cvt_pk_bf16_f32 v128, v122, v123
	v_cvt_pk_bf16_f32 v129, v124, v125
	v_cvt_pk_bf16_f32 v114, v114, v115
	v_cvt_pk_bf16_f32 v115, v116, v117
	v_cvt_pk_bf16_f32 v116, v106, v107
	v_cvt_pk_bf16_f32 v117, v108, v109
	ds_write_b128 v152, v[126:129]
	ds_write_b128 v152, v[114:117] offset:16
	ds_read_b128 v[106:109], v153
	ds_read_b128 v[122:125], v153 offset:1152
	v_cvt_pk_bf16_f32 v118, v118, v119
	v_cvt_pk_bf16_f32 v119, v120, v121
	v_cvt_pk_bf16_f32 v120, v110, v111
	v_cvt_pk_bf16_f32 v121, v112, v113
	v_cvt_pk_bf16_f32 v102, v102, v103
	v_cvt_pk_bf16_f32 v103, v104, v105
	v_cvt_pk_bf16_f32 v104, v94, v95
	v_cvt_pk_bf16_f32 v105, v96, v97
	ds_write_b128 v152, v[118:121]
	ds_write_b128 v152, v[102:105] offset:16
	ds_read_b128 v[94:97], v153
	ds_read_b128 v[110:113], v153 offset:1152
	s_waitcnt lgkmcnt(4)
	v_lshl_add_u64 v[114:115], v[154:155], 0, v[138:139]
	s_mov_b32 s100, 0x30400
	v_lshl_add_u64 v[128:129], v[114:115], 0, s[100:101]
	global_store_dwordx4 v[114:115], v[106:109], off nt
	global_store_dwordx4 v[128:129], v[122:125], off nt
	v_cvt_pk_bf16_f32 v98, v98, v99
	v_cvt_pk_bf16_f32 v99, v100, v101
	v_cvt_pk_bf16_f32 v100, v90, v91
	v_cvt_pk_bf16_f32 v101, v92, v93
	v_cvt_pk_bf16_f32 v86, v86, v87
	v_cvt_pk_bf16_f32 v87, v88, v89
	v_cvt_pk_bf16_f32 v88, v78, v79
	v_cvt_pk_bf16_f32 v89, v80, v81
	ds_write_b128 v152, v[98:101]
	ds_write_b128 v152, v[86:89] offset:16
	ds_read_b128 v[78:81], v153
	ds_read_b128 v[90:93], v153 offset:1152
	s_waitcnt lgkmcnt(4)
	s_mov_b32 s100, 0x60800
	v_lshl_add_u64 v[118:119], v[114:115], 0, s[100:101]
	s_mov_b32 s100, 0x90c00
	v_lshl_add_u64 v[120:121], v[114:115], 0, s[100:101]
	global_store_dwordx4 v[118:119], v[94:97], off nt
	global_store_dwordx4 v[120:121], v[110:113], off nt
	v_cvt_pk_bf16_f32 v82, v82, v83
	v_cvt_pk_bf16_f32 v83, v84, v85
	v_cvt_pk_bf16_f32 v84, v74, v75
	v_cvt_pk_bf16_f32 v85, v76, v77
	v_cvt_pk_bf16_f32 v70, v70, v71
	v_cvt_pk_bf16_f32 v71, v72, v73
	v_cvt_pk_bf16_f32 v72, v66, v67
	v_cvt_pk_bf16_f32 v73, v68, v69
	ds_write_b128 v152, v[82:85]
	ds_write_b128 v152, v[70:73] offset:16
	ds_read_b128 v[66:69], v153
	ds_read_b128 v[74:77], v153 offset:1152
	s_waitcnt lgkmcnt(4)
	s_mov_b32 s100, 0xc1000
	v_lshl_add_u64 v[98:99], v[114:115], 0, s[100:101]
	s_mov_b32 s100, 0xf1400
	v_lshl_add_u64 v[100:101], v[114:115], 0, s[100:101]
	global_store_dwordx4 v[98:99], v[78:81], off nt
	global_store_dwordx4 v[100:101], v[90:93], off nt
	v_cvt_pk_bf16_f32 v62, v62, v63
	v_cvt_pk_bf16_f32 v63, v64, v65
	v_cvt_pk_bf16_f32 v64, v58, v59
	v_cvt_pk_bf16_f32 v65, v60, v61
	v_cvt_pk_bf16_f32 v50, v50, v51
	v_cvt_pk_bf16_f32 v51, v52, v53
	v_cvt_pk_bf16_f32 v52, v42, v43
	v_cvt_pk_bf16_f32 v53, v44, v45
	ds_write_b128 v152, v[62:65]
	ds_write_b128 v152, v[50:53] offset:16
	ds_read_b128 v[42:45], v153
	ds_read_b128 v[58:61], v153 offset:1152
	s_waitcnt lgkmcnt(4)
	s_mov_b32 s100, 0x121800
	v_lshl_add_u64 v[82:83], v[114:115], 0, s[100:101]
	s_mov_b32 s100, 0x151c00
	v_lshl_add_u64 v[84:85], v[114:115], 0, s[100:101]
	global_store_dwordx4 v[82:83], v[66:69], off nt
	global_store_dwordx4 v[84:85], v[74:77], off nt
	v_cvt_pk_bf16_f32 v54, v54, v55
	v_cvt_pk_bf16_f32 v55, v56, v57
	v_cvt_pk_bf16_f32 v56, v46, v47
	v_cvt_pk_bf16_f32 v57, v48, v49
	v_cvt_pk_bf16_f32 v34, v34, v35
	v_cvt_pk_bf16_f32 v35, v36, v37
	v_cvt_pk_bf16_f32 v36, v26, v27
	v_cvt_pk_bf16_f32 v37, v28, v29
	ds_write_b128 v152, v[54:57]
	ds_write_b128 v152, v[34:37] offset:16
	ds_read_b128 v[26:29], v153
	ds_read_b128 v[46:49], v153 offset:1152
	s_waitcnt lgkmcnt(4)
	s_mov_b32 s100, 0x304000
	v_lshl_add_u64 v[62:63], v[114:115], 0, s[100:101]
	s_mov_b32 s100, 0x334400
	v_lshl_add_u64 v[64:65], v[114:115], 0, s[100:101]
	global_store_dwordx4 v[62:63], v[42:45], off nt
	global_store_dwordx4 v[64:65], v[58:61], off nt
	v_cvt_pk_bf16_f32 v38, v38, v39
	v_cvt_pk_bf16_f32 v39, v40, v41
	v_cvt_pk_bf16_f32 v40, v30, v31
	v_cvt_pk_bf16_f32 v41, v32, v33
	v_cvt_pk_bf16_f32 v18, v18, v19
	v_cvt_pk_bf16_f32 v19, v20, v21
	v_cvt_pk_bf16_f32 v20, v10, v11
	v_cvt_pk_bf16_f32 v21, v12, v13
	ds_write_b128 v152, v[38:41]
	ds_write_b128 v152, v[18:21] offset:16
	ds_read_b128 v[10:13], v153
	ds_read_b128 v[30:33], v153 offset:1152
	s_waitcnt lgkmcnt(4)
	s_mov_b32 s100, 0x364800
	v_lshl_add_u64 v[54:55], v[114:115], 0, s[100:101]
	s_mov_b32 s100, 0x394c00
	v_lshl_add_u64 v[56:57], v[114:115], 0, s[100:101]
	global_store_dwordx4 v[54:55], v[26:29], off nt
	global_store_dwordx4 v[56:57], v[46:49], off nt
	v_cvt_pk_bf16_f32 v22, v22, v23
	v_cvt_pk_bf16_f32 v23, v24, v25
	v_cvt_pk_bf16_f32 v24, v14, v15
	v_cvt_pk_bf16_f32 v25, v16, v17
	v_cvt_pk_bf16_f32 v6, v6, v7
	v_cvt_pk_bf16_f32 v7, v8, v9
	v_cvt_pk_bf16_f32 v8, v2, v3
	v_cvt_pk_bf16_f32 v9, v4, v5
	ds_write_b128 v152, v[22:25]
	ds_write_b128 v152, v[6:9] offset:16
	ds_read_b128 v[2:5], v153
	ds_read_b128 v[14:17], v153 offset:1152
	s_waitcnt lgkmcnt(4)
	s_mov_b32 s100, 0x3c5000
	v_lshl_add_u64 v[38:39], v[114:115], 0, s[100:101]
	s_mov_b32 s100, 0x3f5400
	v_lshl_add_u64 v[40:41], v[114:115], 0, s[100:101]
	global_store_dwordx4 v[38:39], v[10:13], off nt
	global_store_dwordx4 v[40:41], v[30:33], off nt
	s_waitcnt lgkmcnt(0)
	s_mov_b32 s100, 0x425800
	v_lshl_add_u64 v[22:23], v[114:115], 0, s[100:101]
	s_mov_b32 s100, 0x455c00
	v_lshl_add_u64 v[24:25], v[114:115], 0, s[100:101]
	global_store_dwordx4 v[22:23], v[2:5], off nt
	global_store_dwordx4 v[24:25], v[14:17], off nt
	s_mov_b32 s11, 0x30000
	s_mov_b32 s11, 0x60000
	s_mov_b32 s11, 0x90000
	s_mov_b32 s11, 0xc1000
	s_mov_b32 s11, 0xf1000
	s_andn2_b64 vcc, exec, s[2:3]
	s_mov_b64 s[2:3], -1
	s_cbranch_vccnz .LBB0_75
	s_andn2_b64 vcc, exec, s[4:5]
	s_cbranch_vccnz .LBB0_74
	s_barrier
	s_branch .LBB0_74

.LBB0_412:
	v_lshl_add_u32 v154, s13, 8, v147
	v_ashrrev_i32_e32 v155, 31, v154
	v_lshlrev_b64 v[154:155], 13, v[154:155]
	s_lshl_b32 s4, s93, 8
	v_lshl_add_u64 v[154:155], s[48:49], 0, v[154:155]
	s_ashr_i32 s5, s4, 31
	v_lshl_add_u64 v[154:155], s[4:5], 1, v[154:155]
	s_mov_b32 s13, s1
	v_lshl_add_u64 v[154:155], v[154:155], 0, s[12:13]
	s_nop 3
	s_mov_b32 s101, 0
	v_cvt_pk_bf16_f32 v124, v124, v125
	v_cvt_pk_bf16_f32 v125, v126, v127
	v_cvt_pk_bf16_f32 v126, v120, v121
	v_cvt_pk_bf16_f32 v127, v122, v123
	v_cvt_pk_bf16_f32 v116, v116, v117
	v_cvt_pk_bf16_f32 v117, v118, v119
	v_cvt_pk_bf16_f32 v118, v112, v113
	v_cvt_pk_bf16_f32 v119, v114, v115
	ds_write_b128 v152, v[124:127]
	ds_write_b128 v152, v[116:119] offset:16
	ds_read_b128 v[112:115], v153
	ds_read_b128 v[120:123], v153 offset:1152
	v_cvt_pk_bf16_f32 v108, v108, v109
	v_cvt_pk_bf16_f32 v109, v110, v111
	v_cvt_pk_bf16_f32 v110, v104, v105
	v_cvt_pk_bf16_f32 v111, v106, v107
	v_cvt_pk_bf16_f32 v100, v100, v101
	v_cvt_pk_bf16_f32 v101, v102, v103
	v_cvt_pk_bf16_f32 v102, v96, v97
	v_cvt_pk_bf16_f32 v103, v98, v99
	ds_write_b128 v152, v[108:111]
	ds_write_b128 v152, v[100:103] offset:16
	ds_read_b128 v[96:99], v153
	ds_read_b128 v[104:107], v153 offset:1152
	s_waitcnt lgkmcnt(4)
	v_lshl_add_u64 v[116:117], v[154:155], 0, v[136:137]
	s_mov_b32 s100, 0x10000
	v_lshl_add_u64 v[126:127], v[116:117], 0, s[100:101]
	global_store_dwordx4 v[116:117], v[112:115], off nt
	global_store_dwordx4 v[126:127], v[120:123], off nt
	v_cvt_pk_bf16_f32 v92, v92, v93
	v_cvt_pk_bf16_f32 v93, v94, v95
	v_cvt_pk_bf16_f32 v94, v88, v89
	v_cvt_pk_bf16_f32 v95, v90, v91
	v_cvt_pk_bf16_f32 v84, v84, v85
	v_cvt_pk_bf16_f32 v85, v86, v87
	v_cvt_pk_bf16_f32 v86, v80, v81
	v_cvt_pk_bf16_f32 v87, v82, v83
	ds_write_b128 v152, v[92:95]
	ds_write_b128 v152, v[84:87] offset:16
	ds_read_b128 v[80:83], v153
	ds_read_b128 v[88:91], v153 offset:1152
	s_waitcnt lgkmcnt(4)
	s_mov_b32 s100, 0x20000
	v_lshl_add_u64 v[108:109], v[116:117], 0, s[100:101]
	s_mov_b32 s100, 0x30000
	v_lshl_add_u64 v[110:111], v[116:117], 0, s[100:101]
	global_store_dwordx4 v[108:109], v[96:99], off nt
	global_store_dwordx4 v[110:111], v[104:107], off nt
	v_cvt_pk_bf16_f32 v76, v76, v77
	v_cvt_pk_bf16_f32 v77, v78, v79
	v_cvt_pk_bf16_f32 v78, v72, v73
	v_cvt_pk_bf16_f32 v79, v74, v75
	v_cvt_pk_bf16_f32 v68, v68, v69
	v_cvt_pk_bf16_f32 v69, v70, v71
	v_cvt_pk_bf16_f32 v70, v64, v65
	v_cvt_pk_bf16_f32 v71, v66, v67
	ds_write_b128 v152, v[76:79]
	ds_write_b128 v152, v[68:71] offset:16
	ds_read_b128 v[64:67], v153
	ds_read_b128 v[72:75], v153 offset:1152
	s_waitcnt lgkmcnt(4)
	s_mov_b32 s100, 0x40000
	v_lshl_add_u64 v[92:93], v[116:117], 0, s[100:101]
	s_mov_b32 s100, 0x50000
	v_lshl_add_u64 v[94:95], v[116:117], 0, s[100:101]
	global_store_dwordx4 v[92:93], v[80:83], off nt
	global_store_dwordx4 v[94:95], v[88:91], off nt
	v_cvt_pk_bf16_f32 v60, v60, v61
	v_cvt_pk_bf16_f32 v61, v62, v63
	v_cvt_pk_bf16_f32 v62, v56, v57
	v_cvt_pk_bf16_f32 v63, v58, v59
	v_cvt_pk_bf16_f32 v52, v52, v53
	v_cvt_pk_bf16_f32 v53, v54, v55
	v_cvt_pk_bf16_f32 v54, v48, v49
	v_cvt_pk_bf16_f32 v55, v50, v51
	ds_write_b128 v152, v[60:63]
	ds_write_b128 v152, v[52:55] offset:16
	ds_read_b128 v[48:51], v153
	ds_read_b128 v[56:59], v153 offset:1152
	s_waitcnt lgkmcnt(4)
	s_mov_b32 s100, 0x60000
	v_lshl_add_u64 v[76:77], v[116:117], 0, s[100:101]
	s_mov_b32 s100, 0x70000
	v_lshl_add_u64 v[78:79], v[116:117], 0, s[100:101]
	global_store_dwordx4 v[76:77], v[64:67], off nt
	global_store_dwordx4 v[78:79], v[72:75], off nt
	v_cvt_pk_bf16_f32 v44, v44, v45
	v_cvt_pk_bf16_f32 v45, v46, v47
	v_cvt_pk_bf16_f32 v46, v40, v41
	v_cvt_pk_bf16_f32 v47, v42, v43
	v_cvt_pk_bf16_f32 v36, v36, v37
	v_cvt_pk_bf16_f32 v37, v38, v39
	v_cvt_pk_bf16_f32 v38, v32, v33
	v_cvt_pk_bf16_f32 v39, v34, v35
	ds_write_b128 v152, v[44:47]
	ds_write_b128 v152, v[36:39] offset:16
	ds_read_b128 v[32:35], v153
	ds_read_b128 v[40:43], v153 offset:1152
	s_waitcnt lgkmcnt(4)
	s_mov_b32 s100, 0x100000
	v_lshl_add_u64 v[60:61], v[116:117], 0, s[100:101]
	s_mov_b32 s100, 0x110000
	v_lshl_add_u64 v[62:63], v[116:117], 0, s[100:101]
	global_store_dwordx4 v[60:61], v[48:51], off nt
	global_store_dwordx4 v[62:63], v[56:59], off nt
	v_cvt_pk_bf16_f32 v28, v28, v29
	v_cvt_pk_bf16_f32 v29, v30, v31
	v_cvt_pk_bf16_f32 v30, v24, v25
	v_cvt_pk_bf16_f32 v31, v26, v27
	v_cvt_pk_bf16_f32 v20, v20, v21
	v_cvt_pk_bf16_f32 v21, v22, v23
	v_cvt_pk_bf16_f32 v22, v16, v17
	v_cvt_pk_bf16_f32 v23, v18, v19
	ds_write_b128 v152, v[28:31]
	ds_write_b128 v152, v[20:23] offset:16
	ds_read_b128 v[16:19], v153
	ds_read_b128 v[24:27], v153 offset:1152
	s_waitcnt lgkmcnt(4)
	s_mov_b32 s100, 0x120000
	v_lshl_add_u64 v[44:45], v[116:117], 0, s[100:101]
	s_mov_b32 s100, 0x130000
	v_lshl_add_u64 v[46:47], v[116:117], 0, s[100:101]
	global_store_dwordx4 v[44:45], v[32:35], off nt
	global_store_dwordx4 v[46:47], v[40:43], off nt
	v_cvt_pk_bf16_f32 v12, v12, v13
	v_cvt_pk_bf16_f32 v13, v14, v15
	v_cvt_pk_bf16_f32 v14, v8, v9
	v_cvt_pk_bf16_f32 v15, v10, v11
	v_cvt_pk_bf16_f32 v4, v4, v5
	v_cvt_pk_bf16_f32 v5, v6, v7
	v_cvt_pk_bf16_f32 v6, v0, v1
	v_cvt_pk_bf16_f32 v7, v2, v3
	ds_write_b128 v152, v[12:15]
	ds_write_b128 v152, v[4:7] offset:16
	ds_read_b128 v[0:3], v153
	ds_read_b128 v[8:11], v153 offset:1152
	s_waitcnt lgkmcnt(4)
	s_mov_b32 s100, 0x140000
	v_lshl_add_u64 v[28:29], v[116:117], 0, s[100:101]
	s_mov_b32 s100, 0x150000
	v_lshl_add_u64 v[30:31], v[116:117], 0, s[100:101]
	global_store_dwordx4 v[28:29], v[16:19], off nt
	global_store_dwordx4 v[30:31], v[24:27], off nt
	s_waitcnt lgkmcnt(0)
	s_mov_b32 s100, 0x160000
	v_lshl_add_u64 v[12:13], v[116:117], 0, s[100:101]
	s_mov_b32 s100, 0x170000
	v_lshl_add_u64 v[14:15], v[116:117], 0, s[100:101]
	global_store_dwordx4 v[12:13], v[0:3], off nt
	global_store_dwordx4 v[14:15], v[8:11], off nt
	s_mov_b32 s4, 0x10000
	s_mov_b32 s4, 0x20000
	s_mov_b32 s4, 0x30000
	s_mov_b32 s4, 0x40000
	s_and_b64 vcc, exec, s[2:3]
	s_mov_b64 s[2:3], -1
	s_cbranch_vccnz .LBB0_397
	s_andn2_b64 vcc, exec, s[6:7]
	s_cbranch_vccnz .LBB0_396
	s_barrier
	s_branch .LBB0_396

.LBB0_548:
	v_lshl_add_u32 v153, s18, 8, v147
	v_mov_b64_e32 v[154:155], s[56:57]
	v_mad_i64_i32 v[154:155], vcc, v153, s66, v[154:155]
	s_lshl_b32 s22, s94, 8
	s_ashr_i32 s23, s22, 31
	v_lshl_add_u64 v[154:155], s[22:23], 1, v[154:155]
	v_lshl_add_u64 v[154:155], v[154:155], 0, s[4:5]
	s_nop 3
	s_mov_b32 s101, 0
	v_cvt_pk_bf16_f32 v124, v124, v125
	v_cvt_pk_bf16_f32 v125, v126, v127
	v_cvt_pk_bf16_f32 v126, v120, v121
	v_cvt_pk_bf16_f32 v127, v122, v123
	v_cvt_pk_bf16_f32 v112, v112, v113
	v_cvt_pk_bf16_f32 v113, v114, v115
	v_cvt_pk_bf16_f32 v114, v104, v105
	v_cvt_pk_bf16_f32 v115, v106, v107
	ds_write_b128 v151, v[124:127]
	ds_write_b128 v151, v[112:115] offset:16
	ds_read_b128 v[104:107], v152
	ds_read_b128 v[120:123], v152 offset:1152
	v_cvt_pk_bf16_f32 v116, v116, v117
	v_cvt_pk_bf16_f32 v117, v118, v119
	v_cvt_pk_bf16_f32 v118, v108, v109
	v_cvt_pk_bf16_f32 v119, v110, v111
	v_cvt_pk_bf16_f32 v96, v96, v97
	v_cvt_pk_bf16_f32 v97, v98, v99
	v_cvt_pk_bf16_f32 v98, v88, v89
	v_cvt_pk_bf16_f32 v99, v90, v91
	ds_write_b128 v151, v[116:119]
	ds_write_b128 v151, v[96:99] offset:16
	ds_read_b128 v[88:91], v152
	ds_read_b128 v[108:111], v152 offset:1152
	s_waitcnt lgkmcnt(4)
	v_lshl_add_u64 v[112:113], v[154:155], 0, v[136:137]
	s_mov_b32 s100, 0x30400
	v_lshl_add_u64 v[126:127], v[112:113], 0, s[100:101]
	global_store_dwordx4 v[112:113], v[104:107], off nt
	global_store_dwordx4 v[126:127], v[120:123], off nt
	v_cvt_pk_bf16_f32 v100, v100, v101
	v_cvt_pk_bf16_f32 v101, v102, v103
	v_cvt_pk_bf16_f32 v102, v92, v93
	v_cvt_pk_bf16_f32 v103, v94, v95
	v_cvt_pk_bf16_f32 v80, v80, v81
	v_cvt_pk_bf16_f32 v81, v82, v83
	v_cvt_pk_bf16_f32 v82, v72, v73
	v_cvt_pk_bf16_f32 v83, v74, v75
	ds_write_b128 v151, v[100:103]
	ds_write_b128 v151, v[80:83] offset:16
	ds_read_b128 v[72:75], v152
	ds_read_b128 v[92:95], v152 offset:1152
	s_waitcnt lgkmcnt(4)
	s_mov_b32 s100, 0x60800
	v_lshl_add_u64 v[116:117], v[112:113], 0, s[100:101]
	s_mov_b32 s100, 0x90c00
	v_lshl_add_u64 v[118:119], v[112:113], 0, s[100:101]
	global_store_dwordx4 v[116:117], v[88:91], off nt
	global_store_dwordx4 v[118:119], v[108:111], off nt
	v_cvt_pk_bf16_f32 v84, v84, v85
	v_cvt_pk_bf16_f32 v85, v86, v87
	v_cvt_pk_bf16_f32 v86, v76, v77
	v_cvt_pk_bf16_f32 v87, v78, v79
	v_cvt_pk_bf16_f32 v68, v68, v69
	v_cvt_pk_bf16_f32 v69, v70, v71
	v_cvt_pk_bf16_f32 v70, v64, v65
	v_cvt_pk_bf16_f32 v71, v66, v67
	ds_write_b128 v151, v[84:87]
	ds_write_b128 v151, v[68:71] offset:16
	ds_read_b128 v[64:67], v152
	ds_read_b128 v[76:79], v152 offset:1152
	s_waitcnt lgkmcnt(4)
	s_mov_b32 s100, 0xc1000
	v_lshl_add_u64 v[100:101], v[112:113], 0, s[100:101]
	s_mov_b32 s100, 0xf1400
	v_lshl_add_u64 v[102:103], v[112:113], 0, s[100:101]
	global_store_dwordx4 v[100:101], v[72:75], off nt
	global_store_dwordx4 v[102:103], v[92:95], off nt
	v_cvt_pk_bf16_f32 v60, v60, v61
	v_cvt_pk_bf16_f32 v61, v62, v63
	v_cvt_pk_bf16_f32 v62, v56, v57
	v_cvt_pk_bf16_f32 v63, v58, v59
	v_cvt_pk_bf16_f32 v48, v48, v49
	v_cvt_pk_bf16_f32 v49, v50, v51
	v_cvt_pk_bf16_f32 v50, v40, v41
	v_cvt_pk_bf16_f32 v51, v42, v43
	ds_write_b128 v151, v[60:63]
	ds_write_b128 v151, v[48:51] offset:16
	ds_read_b128 v[40:43], v152
	ds_read_b128 v[56:59], v152 offset:1152
	s_waitcnt lgkmcnt(4)
	s_mov_b32 s100, 0x121800
	v_lshl_add_u64 v[84:85], v[112:113], 0, s[100:101]
	s_mov_b32 s100, 0x151c00
	v_lshl_add_u64 v[86:87], v[112:113], 0, s[100:101]
	global_store_dwordx4 v[84:85], v[64:67], off nt
	global_store_dwordx4 v[86:87], v[76:79], off nt
	v_cvt_pk_bf16_f32 v52, v52, v53
	v_cvt_pk_bf16_f32 v53, v54, v55
	v_cvt_pk_bf16_f32 v54, v44, v45
	v_cvt_pk_bf16_f32 v55, v46, v47
	v_cvt_pk_bf16_f32 v32, v32, v33
	v_cvt_pk_bf16_f32 v33, v34, v35
	v_cvt_pk_bf16_f32 v34, v24, v25
	v_cvt_pk_bf16_f32 v35, v26, v27
	ds_write_b128 v151, v[52:55]
	ds_write_b128 v151, v[32:35] offset:16
	ds_read_b128 v[24:27], v152
	ds_read_b128 v[44:47], v152 offset:1152
	s_waitcnt lgkmcnt(4)
	s_mov_b32 s100, 0x304000
	v_lshl_add_u64 v[60:61], v[112:113], 0, s[100:101]
	s_mov_b32 s100, 0x334400
	v_lshl_add_u64 v[62:63], v[112:113], 0, s[100:101]
	global_store_dwordx4 v[60:61], v[40:43], off nt
	global_store_dwordx4 v[62:63], v[56:59], off nt
	v_cvt_pk_bf16_f32 v36, v36, v37
	v_cvt_pk_bf16_f32 v37, v38, v39
	v_cvt_pk_bf16_f32 v38, v28, v29
	v_cvt_pk_bf16_f32 v39, v30, v31
	v_cvt_pk_bf16_f32 v16, v16, v17
	v_cvt_pk_bf16_f32 v17, v18, v19
	v_cvt_pk_bf16_f32 v18, v8, v9
	v_cvt_pk_bf16_f32 v19, v10, v11
	ds_write_b128 v151, v[36:39]
	ds_write_b128 v151, v[16:19] offset:16
	ds_read_b128 v[8:11], v152
	ds_read_b128 v[28:31], v152 offset:1152
	s_waitcnt lgkmcnt(4)
	s_mov_b32 s100, 0x364800
	v_lshl_add_u64 v[52:53], v[112:113], 0, s[100:101]
	s_mov_b32 s100, 0x394c00
	v_lshl_add_u64 v[54:55], v[112:113], 0, s[100:101]
	global_store_dwordx4 v[52:53], v[24:27], off nt
	global_store_dwordx4 v[54:55], v[44:47], off nt
	v_cvt_pk_bf16_f32 v20, v20, v21
	v_cvt_pk_bf16_f32 v21, v22, v23
	v_cvt_pk_bf16_f32 v22, v12, v13
	v_cvt_pk_bf16_f32 v23, v14, v15
	v_cvt_pk_bf16_f32 v4, v4, v5
	v_cvt_pk_bf16_f32 v5, v6, v7
	v_cvt_pk_bf16_f32 v6, v0, v1
	v_cvt_pk_bf16_f32 v7, v2, v3
	ds_write_b128 v151, v[20:23]
	ds_write_b128 v151, v[4:7] offset:16
	ds_read_b128 v[0:3], v152
	ds_read_b128 v[12:15], v152 offset:1152
	s_waitcnt lgkmcnt(4)
	s_mov_b32 s100, 0x3c5000
	v_lshl_add_u64 v[36:37], v[112:113], 0, s[100:101]
	s_mov_b32 s100, 0x3f5400
	v_lshl_add_u64 v[38:39], v[112:113], 0, s[100:101]
	global_store_dwordx4 v[36:37], v[8:11], off nt
	global_store_dwordx4 v[38:39], v[28:31], off nt
	s_waitcnt lgkmcnt(0)
	s_mov_b32 s100, 0x425800
	v_lshl_add_u64 v[20:21], v[112:113], 0, s[100:101]
	s_mov_b32 s100, 0x455c00
	v_lshl_add_u64 v[22:23], v[112:113], 0, s[100:101]
	global_store_dwordx4 v[20:21], v[0:3], off nt
	global_store_dwordx4 v[22:23], v[12:15], off nt
	s_andn2_b64 vcc, exec, s[2:3]
	s_mov_b64 s[2:3], -1
	s_cbranch_vccnz .LBB0_541
	s_andn2_b64 vcc, exec, s[6:7]
	s_cbranch_vccnz .LBB0_540
	s_barrier
	s_branch .LBB0_540

.LBB0_900:
	v_lshl_add_u32 v156, s13, 8, v147
	v_mov_b64_e32 v[154:155], s[56:57]
	v_mad_i64_i32 v[154:155], vcc, v156, s40, v[154:155]
	s_lshl_b32 s4, s65, 8
	s_ashr_i32 s5, s4, 31
	v_lshl_add_u64 v[154:155], s[4:5], 1, v[154:155]
	s_mov_b32 s13, s1
	v_lshl_add_u64 v[154:155], v[154:155], 0, s[12:13]
	s_nop 3
	s_mov_b32 s101, 0
	v_cvt_pk_bf16_f32 v124, v124, v125
	v_cvt_pk_bf16_f32 v125, v126, v127
	v_cvt_pk_bf16_f32 v126, v120, v121
	v_cvt_pk_bf16_f32 v127, v122, v123
	v_cvt_pk_bf16_f32 v116, v116, v117
	v_cvt_pk_bf16_f32 v117, v118, v119
	v_cvt_pk_bf16_f32 v118, v112, v113
	v_cvt_pk_bf16_f32 v119, v114, v115
	ds_write_b128 v152, v[124:127]
	ds_write_b128 v152, v[116:119] offset:16
	ds_read_b128 v[112:115], v153
	ds_read_b128 v[120:123], v153 offset:1152
	v_cvt_pk_bf16_f32 v108, v108, v109
	v_cvt_pk_bf16_f32 v109, v110, v111
	v_cvt_pk_bf16_f32 v110, v104, v105
	v_cvt_pk_bf16_f32 v111, v106, v107
	v_cvt_pk_bf16_f32 v100, v100, v101
	v_cvt_pk_bf16_f32 v101, v102, v103
	v_cvt_pk_bf16_f32 v102, v96, v97
	v_cvt_pk_bf16_f32 v103, v98, v99
	ds_write_b128 v152, v[108:111]
	ds_write_b128 v152, v[100:103] offset:16
	ds_read_b128 v[96:99], v153
	ds_read_b128 v[104:107], v153 offset:1152
	s_waitcnt lgkmcnt(4)
	v_lshl_add_u64 v[116:117], v[154:155], 0, v[136:137]
	s_mov_b32 s100, 0x30400
	v_lshl_add_u64 v[126:127], v[116:117], 0, s[100:101]
	global_store_dwordx4 v[116:117], v[112:115], off nt
	global_store_dwordx4 v[126:127], v[120:123], off nt
	v_cvt_pk_bf16_f32 v92, v92, v93
	v_cvt_pk_bf16_f32 v93, v94, v95
	v_cvt_pk_bf16_f32 v94, v88, v89
	v_cvt_pk_bf16_f32 v95, v90, v91
	v_cvt_pk_bf16_f32 v84, v84, v85
	v_cvt_pk_bf16_f32 v85, v86, v87
	v_cvt_pk_bf16_f32 v86, v80, v81
	v_cvt_pk_bf16_f32 v87, v82, v83
	ds_write_b128 v152, v[92:95]
	ds_write_b128 v152, v[84:87] offset:16
	ds_read_b128 v[80:83], v153
	ds_read_b128 v[88:91], v153 offset:1152
	s_waitcnt lgkmcnt(4)
	s_mov_b32 s100, 0x60800
	v_lshl_add_u64 v[108:109], v[116:117], 0, s[100:101]
	s_mov_b32 s100, 0x90c00
	v_lshl_add_u64 v[110:111], v[116:117], 0, s[100:101]
	global_store_dwordx4 v[108:109], v[96:99], off nt
	global_store_dwordx4 v[110:111], v[104:107], off nt
	v_cvt_pk_bf16_f32 v76, v76, v77
	v_cvt_pk_bf16_f32 v77, v78, v79
	v_cvt_pk_bf16_f32 v78, v72, v73
	v_cvt_pk_bf16_f32 v79, v74, v75
	v_cvt_pk_bf16_f32 v68, v68, v69
	v_cvt_pk_bf16_f32 v69, v70, v71
	v_cvt_pk_bf16_f32 v70, v64, v65
	v_cvt_pk_bf16_f32 v71, v66, v67
	ds_write_b128 v152, v[76:79]
	ds_write_b128 v152, v[68:71] offset:16
	ds_read_b128 v[64:67], v153
	ds_read_b128 v[72:75], v153 offset:1152
	s_waitcnt lgkmcnt(4)
	s_mov_b32 s100, 0xc1000
	v_lshl_add_u64 v[92:93], v[116:117], 0, s[100:101]
	s_mov_b32 s100, 0xf1400
	v_lshl_add_u64 v[94:95], v[116:117], 0, s[100:101]
	global_store_dwordx4 v[92:93], v[80:83], off nt
	global_store_dwordx4 v[94:95], v[88:91], off nt
	v_cvt_pk_bf16_f32 v60, v60, v61
	v_cvt_pk_bf16_f32 v61, v62, v63
	v_cvt_pk_bf16_f32 v62, v56, v57
	v_cvt_pk_bf16_f32 v63, v58, v59
	v_cvt_pk_bf16_f32 v52, v52, v53
	v_cvt_pk_bf16_f32 v53, v54, v55
	v_cvt_pk_bf16_f32 v54, v48, v49
	v_cvt_pk_bf16_f32 v55, v50, v51
	ds_write_b128 v152, v[60:63]
	ds_write_b128 v152, v[52:55] offset:16
	ds_read_b128 v[48:51], v153
	ds_read_b128 v[56:59], v153 offset:1152
	s_waitcnt lgkmcnt(4)
	s_mov_b32 s100, 0x121800
	v_lshl_add_u64 v[76:77], v[116:117], 0, s[100:101]
	s_mov_b32 s100, 0x151c00
	v_lshl_add_u64 v[78:79], v[116:117], 0, s[100:101]
	global_store_dwordx4 v[76:77], v[64:67], off nt
	global_store_dwordx4 v[78:79], v[72:75], off nt
	v_cvt_pk_bf16_f32 v44, v44, v45
	v_cvt_pk_bf16_f32 v45, v46, v47
	v_cvt_pk_bf16_f32 v46, v40, v41
	v_cvt_pk_bf16_f32 v47, v42, v43
	v_cvt_pk_bf16_f32 v36, v36, v37
	v_cvt_pk_bf16_f32 v37, v38, v39
	v_cvt_pk_bf16_f32 v38, v32, v33
	v_cvt_pk_bf16_f32 v39, v34, v35
	ds_write_b128 v152, v[44:47]
	ds_write_b128 v152, v[36:39] offset:16
	ds_read_b128 v[32:35], v153
	ds_read_b128 v[40:43], v153 offset:1152
	s_waitcnt lgkmcnt(4)
	s_mov_b32 s100, 0x304000
	v_lshl_add_u64 v[60:61], v[116:117], 0, s[100:101]
	s_mov_b32 s100, 0x334400
	v_lshl_add_u64 v[62:63], v[116:117], 0, s[100:101]
	global_store_dwordx4 v[60:61], v[48:51], off nt
	global_store_dwordx4 v[62:63], v[56:59], off nt
	v_cvt_pk_bf16_f32 v28, v28, v29
	v_cvt_pk_bf16_f32 v29, v30, v31
	v_cvt_pk_bf16_f32 v30, v24, v25
	v_cvt_pk_bf16_f32 v31, v26, v27
	v_cvt_pk_bf16_f32 v20, v20, v21
	v_cvt_pk_bf16_f32 v21, v22, v23
	v_cvt_pk_bf16_f32 v22, v16, v17
	v_cvt_pk_bf16_f32 v23, v18, v19
	ds_write_b128 v152, v[28:31]
	ds_write_b128 v152, v[20:23] offset:16
	ds_read_b128 v[16:19], v153
	ds_read_b128 v[24:27], v153 offset:1152
	s_waitcnt lgkmcnt(4)
	s_mov_b32 s100, 0x364800
	v_lshl_add_u64 v[44:45], v[116:117], 0, s[100:101]
	s_mov_b32 s100, 0x394c00
	v_lshl_add_u64 v[46:47], v[116:117], 0, s[100:101]
	global_store_dwordx4 v[44:45], v[32:35], off nt
	global_store_dwordx4 v[46:47], v[40:43], off nt
	v_cvt_pk_bf16_f32 v12, v12, v13
	v_cvt_pk_bf16_f32 v13, v14, v15
	v_cvt_pk_bf16_f32 v14, v8, v9
	v_cvt_pk_bf16_f32 v15, v10, v11
	v_cvt_pk_bf16_f32 v4, v4, v5
	v_cvt_pk_bf16_f32 v5, v6, v7
	v_cvt_pk_bf16_f32 v6, v0, v1
	v_cvt_pk_bf16_f32 v7, v2, v3
	ds_write_b128 v152, v[12:15]
	ds_write_b128 v152, v[4:7] offset:16
	ds_read_b128 v[0:3], v153
	ds_read_b128 v[8:11], v153 offset:1152
	s_waitcnt lgkmcnt(4)
	s_mov_b32 s100, 0x3c5000
	v_lshl_add_u64 v[28:29], v[116:117], 0, s[100:101]
	s_mov_b32 s100, 0x3f5400
	v_lshl_add_u64 v[30:31], v[116:117], 0, s[100:101]
	global_store_dwordx4 v[28:29], v[16:19], off nt
	global_store_dwordx4 v[30:31], v[24:27], off nt
	s_waitcnt lgkmcnt(0)
	s_mov_b32 s100, 0x425800
	v_lshl_add_u64 v[12:13], v[116:117], 0, s[100:101]
	s_mov_b32 s100, 0x455c00
	v_lshl_add_u64 v[14:15], v[116:117], 0, s[100:101]
	global_store_dwordx4 v[12:13], v[0:3], off nt
	global_store_dwordx4 v[14:15], v[8:11], off nt
	s_and_b64 vcc, exec, s[2:3]
	s_mov_b64 s[2:3], -1
	s_cbranch_vccnz .LBB0_885
	s_andn2_b64 vcc, exec, s[6:7]
	s_cbranch_vccnz .LBB0_884
	s_barrier
	s_branch .LBB0_884
